# P0 row loop: prompt-row kernarg pointers loaded once before the loop (same code size as previous best)
# baseline (speedup 1.0000x reference)
; __device__ __forceinline__ unsigned pk2(float lo, float hi) { f32x2 v = {lo, hi}; bf16x2_t b = __builtin_convertvector(v, bf16x2_t); return __builtin_bit_cast(unsigned, b); }
; __device__ __forceinline__ void rms_row_to_bf16(const float* xrow, const float* gain, bf16* orow, int lane) {
;     f32x4 v[4]; float s = 0.f;
; #pragma unroll
;     for (int j = 0; j < 4; ++j) { v[j] = xrow ? ((const f32x4*)xrow)[lane + 64 * j] : (f32x4){0.f, 0.f, 0.f, 0.f}; s += (v[j].x * v[j].x + v[j].y * v[j].y) + (v[j].z * v[j].z + v[j].w * v[j].w); }
;     const float rstd = 1.f / sqrtf(wave_sum(s) * (1.f / DM) + EPS);
; #pragma unroll
;     for (int j = 0; j < 4; ++j) { const f32x4 g = ((const f32x4*)gain)[lane + 64 * j];
; __device__ __forceinline__ void p0_prologue(const Args& a, LAS unsigned char* lds, int vcu, int G, int tid, int lane, int wave) {
;     ...
;     for (int m0 = gw; m0 < MT; m0 += 2 * NGW)
; #pragma unroll
;     for (int qq = 0; qq < 2; ++qq) { const int m = m0 + qq * NGW; if (m >= MT) break;
;         rms_row_to_bf16(xrow_ptr(a, m, z), (const float*)a.in[I_F1PRE + z], (bf16*)(ws + WS_XN) + (size_t)m * DM, lane);
;         const float* pr = m < MP ? (const float*)a.in[I_PP + z] + (size_t)m * DPLE : (m < MP + NS ? (const float*)a.in[I_PS + z] + (size_t)(m - MP) * DPLE : nullptr);
;         const f32x4 v = pr ? ((const f32x4*)pr)[lane] : (f32x4){0.f, 0.f, 0.f, 0.f};
;         u32x2 o; o.x = pk2(v.x, v.y); o.y = pk2(v.z, v.w);
;         ((u32x2*)((bf16*)(ws + WS_PB) + (size_t)m * DPLE))[lane] = o;
;     }
.LBB0_36:
	s_or_b64 exec, exec, s[12:13]
	s_cmpk_gt_i32 s6, 0x40ff
	s_cbranch_scc1 .LBB0_83
	s_load_dwordx2 s[2:3], s[4:5], 0x48
	s_load_dwordx2 s[98:99], s[4:5], 0x0
	s_load_dwordx2 s[100:101], s[4:5], 0x10
	v_and_b32_e32 v0, 63, v14
	v_mov_b32_e32 v3, 0
	v_lshlrev_b32_e32 v2, 3, v0
	s_waitcnt lgkmcnt(0)
	v_lshl_add_u64 v[4:5], s[8:9], 0, v[2:3]
	v_lshlrev_b32_e32 v2, 4, v0
	s_mov_b64 s[8:9], 0x25100000
	v_lshl_add_u64 v[18:19], s[2:3], 0, v[2:3]
	global_load_dwordx4 v[40:43], v[18:19], off
	global_load_dwordx4 v[44:47], v[18:19], off offset:1024
	global_load_dwordx4 v[48:51], v[18:19], off offset:2048
	global_load_dwordx4 v[52:55], v[18:19], off offset:3072
	s_mov_b64 s[2:3], 0x4000000
	v_lshl_add_u64 v[16:17], v[4:5], 0, s[8:9]
	v_lshl_add_u64 v[20:21], v[4:5], 0, s[2:3]
	s_mov_b32 s9, 0
	v_mov_b32_e32 v22, 0x358637bd
	s_mov_b32 s16, 0xf800000
	v_mov_b32_e32 v23, 0x260
	v_lshlrev_b32_e32 v24, 4, v0
	s_waitcnt vmcnt(0)
	s_branch .LBB0_42

; __device__ __forceinline__ const float* xrow_ptr(const Args& a, int m, int z) {
;     if (m < MP) return (const float*)a.in[I_XP + z] + (size_t)m * DM;
;     if (m < MP + NS) return (const float*)a.in[I_XS + z] + (size_t)(m - MP) * DM;
.LBB0_45:
	s_andn2_b64 vcc, exec, s[2:3]
	s_cbranch_vccnz .LBB0_47
	s_mov_b64 s[2:3], s[98:99]
	s_ashr_i32 s7, s6, 31
	s_lshl_b64 s[12:13], s[6:7], 12
	s_waitcnt lgkmcnt(0)
	s_add_u32 s12, s2, s12
	s_addc_u32 s13, s3, s13

; __device__ __forceinline__ void p0_prologue(const Args& a, LAS unsigned char* lds, int vcu, int G, int tid, int lane, int wave) {
;     ...
;     for (int qq = 0; qq < 2; ++qq) { const int m = m0 + qq * NGW; if (m >= MT) break;
;         rms_row_to_bf16(xrow_ptr(a, m, z), (const float*)a.in[I_F1PRE + z], (bf16*)(ws + WS_XN) + (size_t)m * DM, lane);
;         const float* pr = m < MP ? (const float*)a.in[I_PP + z] + (size_t)m * DPLE : (m < MP + NS ? (const float*)a.in[I_PS + z] + (size_t)(m - MP) * DPLE : nullptr);
;         const f32x4 v = pr ? ((const f32x4*)pr)[lane] : (f32x4){0.f, 0.f, 0.f, 0.f};
.LBB0_58:
	s_andn2_b64 vcc, exec, s[12:13]
	s_cbranch_vccnz .LBB0_60
	s_mov_b64 s[2:3], s[100:101]
	s_lshl_b64 s[10:11], s[6:7], 10
	s_waitcnt lgkmcnt(0)
	s_add_u32 s2, s2, s10
	s_addc_u32 s3, s3, s11

; __device__ __forceinline__ void p0_prologue(const Args& a, LAS unsigned char* lds, int vcu, int G, int tid, int lane, int wave) {
;     ...
;     for (int qq = 0; qq < 2; ++qq) { const int m = m0 + qq * NGW; if (m >= MT) break;
;         rms_row_to_bf16(xrow_ptr(a, m, z), (const float*)a.in[I_F1PRE + z], (bf16*)(ws + WS_XN) + (size_t)m * DM, lane);
;         const float* pr = m < MP ? (const float*)a.in[I_PP + z] + (size_t)m * DPLE : (m < MP + NS ? (const float*)a.in[I_PS + z] + (size_t)(m - MP) * DPLE : nullptr);
;         const f32x4 v = pr ? ((const f32x4*)pr)[lane] : (f32x4){0.f, 0.f, 0.f, 0.f};
.LBB0_80:
	s_andn2_b64 vcc, exec, s[10:11]
	s_cbranch_vccnz .LBB0_38
	s_mov_b64 s[2:3], s[100:101]
	s_lshl_b64 s[10:11], s[6:7], 10
	s_waitcnt lgkmcnt(0)
	s_add_u32 s2, s2, s10
	s_addc_u32 s3, s3, s11
	s_branch .LBB0_38

; __global__ void __launch_bounds__(NWAVES * 64, 2) hybrid_fwd(Args args) {
	.amdhsa_kernel _Z10hybrid_fwd4Args
		.amdhsa_group_segment_fixed_size 0
		.amdhsa_private_segment_fixed_size 0
		.amdhsa_kernarg_size 616
		.amdhsa_user_sgpr_count 2
		.amdhsa_user_sgpr_dispatch_ptr 0
		.amdhsa_user_sgpr_queue_ptr 0
		.amdhsa_user_sgpr_kernarg_segment_ptr 1
		.amdhsa_user_sgpr_dispatch_id 0
		.amdhsa_user_sgpr_kernarg_preload_length 0
		.amdhsa_user_sgpr_kernarg_preload_offset 0
		.amdhsa_user_sgpr_private_segment_size 0
		.amdhsa_uses_dynamic_stack 0
		.amdhsa_enable_private_segment 0
		.amdhsa_system_sgpr_workgroup_id_x 1
		.amdhsa_system_sgpr_workgroup_id_y 0
		.amdhsa_system_sgpr_workgroup_id_z 0
		.amdhsa_system_sgpr_workgroup_info 0
		.amdhsa_system_vgpr_workitem_id 0
		.amdhsa_next_free_vgpr 256
		.amdhsa_next_free_sgpr 102
		.amdhsa_accum_offset 256
		.amdhsa_reserve_vcc 1
		.amdhsa_float_round_mode_32 0
		.amdhsa_float_round_mode_16_64 0
		.amdhsa_float_denorm_mode_32 3
		.amdhsa_float_denorm_mode_16_64 3
		.amdhsa_dx10_clamp 1
		.amdhsa_ieee_mode 1
		.amdhsa_fp16_overflow 0
		.amdhsa_tg_split 0
		.amdhsa_exception_fp_ieee_invalid_op 0
		.amdhsa_exception_fp_denorm_src 0
		.amdhsa_exception_fp_ieee_div_zero 0
		.amdhsa_exception_fp_ieee_overflow 0
		.amdhsa_exception_fp_ieee_underflow 0
		.amdhsa_exception_fp_ieee_inexact 0
		.amdhsa_exception_int_div_zero 0
	.end_amdhsa_kernel

; __global__ void __launch_bounds__(NWAVES * 64, 2) hybrid_fwd(Args args) {
amdhsa.kernels:
  - .agpr_count:     0
    .args:
      - .offset:         0
        .size:           360
        .value_kind:     by_value
      - .offset:         360
        .size:           4
        .value_kind:     hidden_block_count_x
      - .offset:         364
        .size:           4
        .value_kind:     hidden_block_count_y
      - .offset:         368
        .size:           4
        .value_kind:     hidden_block_count_z
      - .offset:         372
        .size:           2
        .value_kind:     hidden_group_size_x
      - .offset:         374
        .size:           2
        .value_kind:     hidden_group_size_y
      - .offset:         376
        .size:           2
        .value_kind:     hidden_group_size_z
      - .offset:         378
        .size:           2
        .value_kind:     hidden_remainder_x
      - .offset:         380
        .size:           2
        .value_kind:     hidden_remainder_y
      - .offset:         382
        .size:           2
        .value_kind:     hidden_remainder_z
      - .offset:         400
        .size:           8
        .value_kind:     hidden_global_offset_x
      - .offset:         408
        .size:           8
        .value_kind:     hidden_global_offset_y
      - .offset:         416
        .size:           8
        .value_kind:     hidden_global_offset_z
      - .offset:         424
        .size:           2
        .value_kind:     hidden_grid_dims
      - .offset:         480
        .size:           4
        .value_kind:     hidden_dynamic_lds_size
    .group_segment_fixed_size: 0
    .kernarg_segment_align: 8
    .kernarg_segment_size: 616
    .language:       OpenCL C
    .language_version:
      - 2
      - 0
    .max_flat_workgroup_size: 512
    .name:           _Z10hybrid_fwd4Args
    .private_segment_fixed_size: 0
    .sgpr_count:     108
    .sgpr_spill_count: 64
    .symbol:         _Z10hybrid_fwd4Args.kd
    .uniform_work_group_size: 1
    .uses_dynamic_stack: false
    .vgpr_count:     256
    .vgpr_spill_count: 0
    .wavefront_size: 64
